# GEMM unit loops (up, in-proj main, resid): dropped the compiler's vmcnt(0) store drain in the accumulator-zeroing block at each unit start
# baseline (speedup 1.0000x reference)
.LBB0_105:
	s_ashr_i32 s71, s70, 31
	s_lshl_b64 s[6:7], s[70:71], 19
	v_readlane_b32 s28, v254, 41
	v_readlane_b32 s29, v254, 42
	s_add_u32 s72, s28, s6
	s_addc_u32 s73, s29, s7
	s_and_b64 s[6:7], s[40:41], exec
	s_cselect_b32 s6, s73, s5
	s_cselect_b32 s7, s72, s4
	s_ashr_i32 s69, s68, 31
	s_lshl_b64 s[28:29], s[68:69], 19
	s_add_u32 s74, s9, s28
	s_addc_u32 s75, s10, s29
	s_and_b64 s[28:29], s[40:41], exec
	s_cselect_b32 s27, s75, s1
	s_cselect_b32 s28, s74, s0
	s_add_u32 s42, s4, 0x40080
	s_addc_u32 s43, s5, 0
	s_add_u32 s29, s0, 0x100
	v_mov_b32_e32 v14, 0
	s_addc_u32 s34, s1, 0
	s_mov_b32 s35, -2
	v_mov_b32_e32 v15, v14
	v_mov_b32_e32 v16, v14
	v_mov_b32_e32 v17, v14
	v_mov_b32_e32 v82, v14
	v_mov_b32_e32 v83, v14
	v_mov_b32_e32 v84, v14
	v_mov_b32_e32 v85, v14
	v_mov_b32_e32 v2, v14
	v_mov_b32_e32 v3, v14
	v_mov_b32_e32 v4, v14
	v_mov_b32_e32 v5, v14
	v_mov_b32_e32 v66, v14
	v_mov_b32_e32 v67, v14
	v_mov_b32_e32 v68, v14
	v_mov_b32_e32 v69, v14
	v_mov_b32_e32 v6, v14
	v_mov_b32_e32 v7, v14
	v_mov_b32_e32 v8, v14
	v_mov_b32_e32 v9, v14
	v_mov_b32_e32 v70, v14
	v_mov_b32_e32 v71, v14
	v_mov_b32_e32 v72, v14
	v_mov_b32_e32 v73, v14
	v_mov_b32_e32 v26, v14
	v_mov_b32_e32 v27, v14
	v_mov_b32_e32 v28, v14
	v_mov_b32_e32 v29, v14
	v_mov_b32_e32 v90, v14
	v_mov_b32_e32 v91, v14
	v_mov_b32_e32 v92, v14
	v_mov_b32_e32 v93, v14
	v_mov_b32_e32 v22, v14
	v_mov_b32_e32 v23, v14
	v_mov_b32_e32 v24, v14
	v_mov_b32_e32 v25, v14
	v_mov_b32_e32 v86, v14
	v_mov_b32_e32 v87, v14
	v_mov_b32_e32 v88, v14
	v_mov_b32_e32 v89, v14
	v_mov_b32_e32 v10, v14
	v_mov_b32_e32 v11, v14
	v_mov_b32_e32 v12, v14
	v_mov_b32_e32 v13, v14
	v_mov_b32_e32 v74, v14
	v_mov_b32_e32 v75, v14
	v_mov_b32_e32 v76, v14
	v_mov_b32_e32 v77, v14
	v_mov_b32_e32 v18, v14
	v_mov_b32_e32 v19, v14
	v_mov_b32_e32 v20, v14
	v_mov_b32_e32 v21, v14
	v_mov_b32_e32 v78, v14
	v_mov_b32_e32 v79, v14
	v_mov_b32_e32 v80, v14
	v_mov_b32_e32 v81, v14
	v_mov_b32_e32 v30, v14
	v_mov_b32_e32 v31, v14
	v_mov_b32_e32 v32, v14
	v_mov_b32_e32 v33, v14
	v_mov_b32_e32 v94, v14
	v_mov_b32_e32 v95, v14
	v_mov_b32_e32 v96, v14
	v_mov_b32_e32 v97, v14
	v_mov_b32_e32 v50, v14
	v_mov_b32_e32 v51, v14
	v_mov_b32_e32 v52, v14
	v_mov_b32_e32 v53, v14
	v_mov_b32_e32 v114, v14
	v_mov_b32_e32 v115, v14
	v_mov_b32_e32 v116, v14
	v_mov_b32_e32 v117, v14
	v_mov_b32_e32 v34, v14
	v_mov_b32_e32 v35, v14
	v_mov_b32_e32 v36, v14
	v_mov_b32_e32 v37, v14
	v_mov_b32_e32 v98, v14
	v_mov_b32_e32 v99, v14
	v_mov_b32_e32 v100, v14
	v_mov_b32_e32 v101, v14
	v_mov_b32_e32 v38, v14
	v_mov_b32_e32 v39, v14
	v_mov_b32_e32 v40, v14
	v_mov_b32_e32 v41, v14
	v_mov_b32_e32 v102, v14
	v_mov_b32_e32 v103, v14
	v_mov_b32_e32 v104, v14
	v_mov_b32_e32 v105, v14
	v_mov_b32_e32 v58, v14
	v_mov_b32_e32 v59, v14
	v_mov_b32_e32 v60, v14
	v_mov_b32_e32 v61, v14
	v_mov_b32_e32 v122, v14
	v_mov_b32_e32 v123, v14
	v_mov_b32_e32 v124, v14
	v_mov_b32_e32 v125, v14
	v_mov_b32_e32 v54, v14
	v_mov_b32_e32 v55, v14
	v_mov_b32_e32 v56, v14
	v_mov_b32_e32 v57, v14
	v_mov_b32_e32 v118, v14
	v_mov_b32_e32 v119, v14
	v_mov_b32_e32 v120, v14
	v_mov_b32_e32 v121, v14
	v_mov_b32_e32 v42, v14
	v_mov_b32_e32 v43, v14
	v_mov_b32_e32 v44, v14
	v_mov_b32_e32 v45, v14
	v_mov_b32_e32 v106, v14
	v_mov_b32_e32 v107, v14
	v_mov_b32_e32 v108, v14
	v_mov_b32_e32 v109, v14
	v_mov_b32_e32 v46, v14
	v_mov_b32_e32 v47, v14
	v_mov_b32_e32 v48, v14
	v_mov_b32_e32 v49, v14
	v_mov_b32_e32 v110, v14
	v_mov_b32_e32 v111, v14
	v_mov_b32_e32 v112, v14
	v_mov_b32_e32 v113, v14
	v_mov_b32_e32 v62, v14
	v_mov_b32_e32 v63, v14
	v_mov_b32_e32 v64, v14
	v_mov_b32_e32 v65, v14
	v_mov_b32_e32 v126, v14
	v_mov_b32_e32 v127, v14
	v_mov_b32_e32 v128, v14
	v_mov_b32_e32 v129, v14
	s_mov_b64 s[80:81], 0x80

.LBB0_661:
	s_add_u32 s25, s0, 0x100
	v_mov_b32_e32 v2, 0
	s_addc_u32 s26, s1, 0
	s_mov_b32 s27, -2
	s_waitcnt lgkmcnt(0)
	v_mov_b32_e32 v3, v2
	v_mov_b32_e32 v4, v2
	v_mov_b32_e32 v5, v2
	v_mov_b32_e32 v6, v2
	v_mov_b32_e32 v7, v2
	v_mov_b32_e32 v8, v2
	v_mov_b32_e32 v9, v2
	v_mov_b32_e32 v18, v2
	v_mov_b32_e32 v19, v2
	v_mov_b32_e32 v20, v2
	v_mov_b32_e32 v21, v2
	v_mov_b32_e32 v22, v2
	v_mov_b32_e32 v23, v2
	v_mov_b32_e32 v24, v2
	v_mov_b32_e32 v25, v2
	v_mov_b32_e32 v34, v2
	v_mov_b32_e32 v35, v2
	v_mov_b32_e32 v36, v2
	v_mov_b32_e32 v37, v2
	v_mov_b32_e32 v38, v2
	v_mov_b32_e32 v39, v2
	v_mov_b32_e32 v40, v2
	v_mov_b32_e32 v41, v2
	v_mov_b32_e32 v50, v2
	v_mov_b32_e32 v51, v2
	v_mov_b32_e32 v52, v2
	v_mov_b32_e32 v53, v2
	v_mov_b32_e32 v54, v2
	v_mov_b32_e32 v55, v2
	v_mov_b32_e32 v56, v2
	v_mov_b32_e32 v57, v2
	v_mov_b32_e32 v10, v2
	v_mov_b32_e32 v11, v2
	v_mov_b32_e32 v12, v2
	v_mov_b32_e32 v13, v2
	v_mov_b32_e32 v14, v2
	v_mov_b32_e32 v15, v2
	v_mov_b32_e32 v16, v2
	v_mov_b32_e32 v17, v2
	v_mov_b32_e32 v26, v2
	v_mov_b32_e32 v27, v2
	v_mov_b32_e32 v28, v2
	v_mov_b32_e32 v29, v2
	v_mov_b32_e32 v30, v2
	v_mov_b32_e32 v31, v2
	v_mov_b32_e32 v32, v2
	v_mov_b32_e32 v33, v2
	v_mov_b32_e32 v42, v2
	v_mov_b32_e32 v43, v2
	v_mov_b32_e32 v44, v2
	v_mov_b32_e32 v45, v2
	v_mov_b32_e32 v46, v2
	v_mov_b32_e32 v47, v2
	v_mov_b32_e32 v48, v2
	v_mov_b32_e32 v49, v2
	v_mov_b32_e32 v58, v2
	v_mov_b32_e32 v59, v2
	v_mov_b32_e32 v60, v2
	v_mov_b32_e32 v61, v2
	v_mov_b32_e32 v62, v2
	v_mov_b32_e32 v63, v2
	v_mov_b32_e32 v64, v2
	v_mov_b32_e32 v65, v2
	v_mov_b32_e32 v66, v2
	v_mov_b32_e32 v67, v2
	v_mov_b32_e32 v68, v2
	v_mov_b32_e32 v69, v2
	v_mov_b32_e32 v70, v2
	v_mov_b32_e32 v71, v2
	v_mov_b32_e32 v72, v2
	v_mov_b32_e32 v73, v2
	v_mov_b32_e32 v82, v2
	v_mov_b32_e32 v83, v2
	v_mov_b32_e32 v84, v2
	v_mov_b32_e32 v85, v2
	v_mov_b32_e32 v86, v2
	v_mov_b32_e32 v87, v2
	v_mov_b32_e32 v88, v2
	v_mov_b32_e32 v89, v2
	v_mov_b32_e32 v98, v2
	v_mov_b32_e32 v99, v2
	v_mov_b32_e32 v100, v2
	v_mov_b32_e32 v101, v2
	v_mov_b32_e32 v102, v2
	v_mov_b32_e32 v103, v2
	v_mov_b32_e32 v104, v2
	v_mov_b32_e32 v105, v2
	v_mov_b32_e32 v138, v2
	v_mov_b32_e32 v139, v2
	v_mov_b32_e32 v140, v2
	v_mov_b32_e32 v141, v2
	v_mov_b32_e32 v142, v2
	v_mov_b32_e32 v143, v2
	v_mov_b32_e32 v144, v2
	v_mov_b32_e32 v145, v2
	v_mov_b32_e32 v74, v2
	v_mov_b32_e32 v75, v2
	v_mov_b32_e32 v76, v2
	v_mov_b32_e32 v77, v2
	v_mov_b32_e32 v78, v2
	v_mov_b32_e32 v79, v2
	v_mov_b32_e32 v80, v2
	v_mov_b32_e32 v81, v2
	v_mov_b32_e32 v90, v2
	v_mov_b32_e32 v91, v2
	v_mov_b32_e32 v92, v2
	v_mov_b32_e32 v93, v2
	v_mov_b32_e32 v94, v2
	v_mov_b32_e32 v95, v2
	v_mov_b32_e32 v96, v2
	v_mov_b32_e32 v97, v2
	v_mov_b32_e32 v106, v2
	v_mov_b32_e32 v107, v2
	v_mov_b32_e32 v108, v2
	v_mov_b32_e32 v109, v2
	v_mov_b32_e32 v110, v2
	v_mov_b32_e32 v111, v2
	v_mov_b32_e32 v112, v2
	v_mov_b32_e32 v113, v2
	v_mov_b32_e32 v146, v2
	v_mov_b32_e32 v147, v2
	v_mov_b32_e32 v148, v2
	v_mov_b32_e32 v149, v2
	v_mov_b32_e32 v150, v2
	v_mov_b32_e32 v151, v2
	v_mov_b32_e32 v152, v2
	v_mov_b32_e32 v153, v2
	s_mov_b64 s[60:61], 0x80
.LBB0_662:
	s_add_u32 s0, s56, 0x100
	s_addc_u32 s1, s57, 0
	s_add_i32 s28, 0, 0x10000
	s_cmp_eq_u32 s27, 40
	s_cselect_b32 s5, s45, s1
	s_cselect_b32 s4, s44, s0
	s_cselect_b32 s3, s55, s26
	s_cselect_b32 s2, s54, s25
	s_add_i32 s34, 0, 0x14000
	v_add_u32_e32 v126, s28, v189
	v_add_u32_e32 v178, s34, v189
	ds_read_b128 v[114:117], v126
	ds_read_b128 v[118:121], v126 offset:1024
	ds_read_b128 v[122:125], v126 offset:2048
	ds_read_b128 v[126:129], v126 offset:3072
	ds_read_b128 v[130:133], v178
	ds_read_b128 v[134:137], v178 offset:1024
	ds_read_b128 v[174:177], v178 offset:2048
	ds_read_b128 v[178:181], v178 offset:3072
	v_lshl_add_u64 v[186:187], s[56:57], 0, v[170:171]
	s_add_i32 m0, s14, 0xc000
	ds_read_b128 v[182:185], v191
	ds_read_b128 v[192:195], v191 offset:1024
	ds_read_b128 v[196:199], v191 offset:2048
	ds_read_b128 v[200:203], v191 offset:3072
	ds_read_b128 v[204:207], v191 offset:4096
	ds_read_b128 v[224:227], v191 offset:5120
	ds_read_b128 v[228:231], v191 offset:6144
	ds_read_b128 v[232:235], v191 offset:7168
	global_load_lds_dwordx4 v[186:187], off
	v_lshl_add_u64 v[186:187], s[56:57], 0, v[172:173]
	s_add_i32 m0, s14, 0xe000
	s_nop 0
	global_load_lds_dwordx4 v[186:187], off
	s_waitcnt vmcnt(8)
	s_waitcnt lgkmcnt(0)
	s_barrier
	s_setprio 1
	s_waitcnt lgkmcnt(0)
	v_mfma_f32_16x16x32_bf16 v[150:153], v[114:117], v[182:185], v[150:153]
	v_mfma_f32_16x16x32_bf16 v[146:149], v[122:125], v[182:185], v[146:149]
	v_mfma_f32_16x16x32_bf16 v[110:113], v[114:117], v[196:199], v[110:113]
	v_mfma_f32_16x16x32_bf16 v[106:109], v[122:125], v[196:199], v[106:109]
	v_mfma_f32_16x16x32_bf16 v[94:97], v[114:117], v[204:207], v[94:97]
	v_mfma_f32_16x16x32_bf16 v[90:93], v[122:125], v[204:207], v[90:93]
	v_mfma_f32_16x16x32_bf16 v[78:81], v[114:117], v[228:231], v[78:81]
	v_mfma_f32_16x16x32_bf16 v[74:77], v[122:125], v[228:231], v[74:77]
	v_mfma_f32_16x16x32_bf16 v[150:153], v[118:121], v[192:195], v[150:153]
	v_mfma_f32_16x16x32_bf16 v[146:149], v[126:129], v[192:195], v[146:149]
	v_mfma_f32_16x16x32_bf16 v[110:113], v[118:121], v[200:203], v[110:113]
	v_mfma_f32_16x16x32_bf16 v[106:109], v[126:129], v[200:203], v[106:109]
	v_mfma_f32_16x16x32_bf16 v[94:97], v[118:121], v[224:227], v[94:97]
	v_mfma_f32_16x16x32_bf16 v[90:93], v[126:129], v[224:227], v[90:93]
	v_mfma_f32_16x16x32_bf16 v[78:81], v[118:121], v[232:235], v[78:81]
	v_mfma_f32_16x16x32_bf16 v[74:77], v[126:129], v[232:235], v[74:77]
	s_setprio 0
	s_setprio 1
	v_mfma_f32_16x16x32_bf16 v[142:145], v[130:133], v[182:185], v[142:145]
	v_mfma_f32_16x16x32_bf16 v[138:141], v[174:177], v[182:185], v[138:141]
	v_mfma_f32_16x16x32_bf16 v[102:105], v[130:133], v[196:199], v[102:105]
	v_mfma_f32_16x16x32_bf16 v[98:101], v[174:177], v[196:199], v[98:101]
	v_mfma_f32_16x16x32_bf16 v[86:89], v[130:133], v[204:207], v[86:89]
	v_mfma_f32_16x16x32_bf16 v[82:85], v[174:177], v[204:207], v[82:85]
	v_mfma_f32_16x16x32_bf16 v[70:73], v[130:133], v[228:231], v[70:73]
	v_mfma_f32_16x16x32_bf16 v[66:69], v[174:177], v[228:231], v[66:69]
	v_mfma_f32_16x16x32_bf16 v[142:145], v[134:137], v[192:195], v[142:145]
	v_mfma_f32_16x16x32_bf16 v[138:141], v[178:181], v[192:195], v[138:141]
	v_mfma_f32_16x16x32_bf16 v[102:105], v[134:137], v[200:203], v[102:105]
	v_mfma_f32_16x16x32_bf16 v[98:101], v[178:181], v[200:203], v[98:101]
	v_mfma_f32_16x16x32_bf16 v[86:89], v[134:137], v[224:227], v[86:89]
	v_mfma_f32_16x16x32_bf16 v[82:85], v[178:181], v[224:227], v[82:85]
	v_mfma_f32_16x16x32_bf16 v[70:73], v[134:137], v[232:235], v[70:73]
	v_mfma_f32_16x16x32_bf16 v[66:69], v[178:181], v[232:235], v[66:69]
	s_setprio 0
	s_barrier
	s_add_i32 s28, s28, s13
	v_lshl_add_u64 v[186:187], s[2:3], 0, v[0:1]
	s_mov_b32 m0, s28
	ds_read_b128 v[182:185], v191 offset:16384
	ds_read_b128 v[192:195], v191 offset:17408
	ds_read_b128 v[196:199], v191 offset:18432
	ds_read_b128 v[200:203], v191 offset:19456
	ds_read_b128 v[204:207], v191 offset:20480
	ds_read_b128 v[224:227], v191 offset:21504
	ds_read_b128 v[228:231], v191 offset:22528
	ds_read_b128 v[232:235], v191 offset:23552
	global_load_lds_dwordx4 v[186:187], off
	s_add_i32 m0, s28, 0x2000
	s_add_u32 s28, s2, 0xb0000
	v_lshl_add_u64 v[236:237], s[2:3], 0, v[158:159]
	s_addc_u32 s29, s3, 0
	s_add_i32 s34, s34, s13
	global_load_lds_dwordx4 v[236:237], off
	v_lshl_add_u64 v[238:239], s[28:29], 0, v[0:1]
	s_mov_b32 m0, s34
	v_lshl_add_u64 v[240:241], s[4:5], 0, v[156:157]
	global_load_lds_dwordx4 v[238:239], off
	v_lshl_add_u64 v[238:239], s[28:29], 0, v[158:159]
	s_add_i32 m0, s34, 0x2000
	s_nop 0
	global_load_lds_dwordx4 v[238:239], off
	v_lshl_add_u64 v[238:239], s[4:5], 0, v[154:155]
	s_mov_b32 m0, s14
	s_nop 0
	global_load_lds_dwordx4 v[238:239], off
	s_mov_b32 m0, s15
	s_nop 0
	global_load_lds_dwordx4 v[240:241], off
	s_waitcnt vmcnt(8)
	s_waitcnt lgkmcnt(0)
	s_barrier
	s_setprio 1
	s_waitcnt lgkmcnt(0)
	v_mfma_f32_16x16x32_bf16 v[62:65], v[114:117], v[182:185], v[62:65]
	v_mfma_f32_16x16x32_bf16 v[58:61], v[122:125], v[182:185], v[58:61]
	v_mfma_f32_16x16x32_bf16 v[46:49], v[114:117], v[196:199], v[46:49]
	v_mfma_f32_16x16x32_bf16 v[42:45], v[122:125], v[196:199], v[42:45]
	v_mfma_f32_16x16x32_bf16 v[30:33], v[114:117], v[204:207], v[30:33]
	v_mfma_f32_16x16x32_bf16 v[26:29], v[122:125], v[204:207], v[26:29]
	v_mfma_f32_16x16x32_bf16 v[14:17], v[114:117], v[228:231], v[14:17]
	v_mfma_f32_16x16x32_bf16 v[10:13], v[122:125], v[228:231], v[10:13]
	v_mfma_f32_16x16x32_bf16 v[62:65], v[118:121], v[192:195], v[62:65]
	v_mfma_f32_16x16x32_bf16 v[58:61], v[126:129], v[192:195], v[58:61]
	v_mfma_f32_16x16x32_bf16 v[46:49], v[118:121], v[200:203], v[46:49]
	v_mfma_f32_16x16x32_bf16 v[42:45], v[126:129], v[200:203], v[42:45]
	v_mfma_f32_16x16x32_bf16 v[30:33], v[118:121], v[224:227], v[30:33]
	v_mfma_f32_16x16x32_bf16 v[26:29], v[126:129], v[224:227], v[26:29]
	v_mfma_f32_16x16x32_bf16 v[14:17], v[118:121], v[232:235], v[14:17]
	v_mfma_f32_16x16x32_bf16 v[10:13], v[126:129], v[232:235], v[10:13]
	s_setprio 0
	s_setprio 1
	v_mfma_f32_16x16x32_bf16 v[54:57], v[130:133], v[182:185], v[54:57]
	v_mfma_f32_16x16x32_bf16 v[50:53], v[174:177], v[182:185], v[50:53]
	v_mfma_f32_16x16x32_bf16 v[38:41], v[130:133], v[196:199], v[38:41]
	v_mfma_f32_16x16x32_bf16 v[34:37], v[174:177], v[196:199], v[34:37]
	v_mfma_f32_16x16x32_bf16 v[22:25], v[130:133], v[204:207], v[22:25]
	v_mfma_f32_16x16x32_bf16 v[18:21], v[174:177], v[204:207], v[18:21]
	v_mfma_f32_16x16x32_bf16 v[6:9], v[130:133], v[228:231], v[6:9]
	v_mfma_f32_16x16x32_bf16 v[2:5], v[174:177], v[228:231], v[2:5]
	v_mfma_f32_16x16x32_bf16 v[54:57], v[134:137], v[192:195], v[54:57]
	v_mfma_f32_16x16x32_bf16 v[50:53], v[178:181], v[192:195], v[50:53]
	v_mfma_f32_16x16x32_bf16 v[38:41], v[134:137], v[200:203], v[38:41]
	v_mfma_f32_16x16x32_bf16 v[34:37], v[178:181], v[200:203], v[34:37]
	v_mfma_f32_16x16x32_bf16 v[22:25], v[134:137], v[224:227], v[22:25]
	v_mfma_f32_16x16x32_bf16 v[18:21], v[178:181], v[224:227], v[18:21]
	v_mfma_f32_16x16x32_bf16 v[6:9], v[134:137], v[232:235], v[6:9]
	v_mfma_f32_16x16x32_bf16 v[2:5], v[178:181], v[232:235], v[2:5]
	s_setprio 0
	s_barrier
	s_add_i32 s28, 0, 0x18000
	s_add_i32 s29, 0, 0x1c000
	v_add_u32_e32 v126, s28, v189
	v_add_u32_e32 v178, s29, v189
	ds_read_b128 v[114:117], v126
	ds_read_b128 v[118:121], v126 offset:1024
	ds_read_b128 v[122:125], v126 offset:2048
	ds_read_b128 v[126:129], v126 offset:3072
	ds_read_b128 v[130:133], v178
	ds_read_b128 v[134:137], v178 offset:1024
	ds_read_b128 v[174:177], v178 offset:2048
	ds_read_b128 v[178:181], v178 offset:3072
	s_add_u32 s4, s4, 0xb0000
	s_addc_u32 s5, s5, 0
	s_mov_b32 m0, s16
	v_lshl_add_u64 v[242:243], s[4:5], 0, v[154:155]
	ds_read_b128 v[182:185], v191 offset:32768
	ds_read_b128 v[192:195], v191 offset:33792
	ds_read_b128 v[196:199], v191 offset:34816
	ds_read_b128 v[200:203], v191 offset:35840
	ds_read_b128 v[204:207], v191 offset:36864
	ds_read_b128 v[224:227], v191 offset:37888
	ds_read_b128 v[228:231], v191 offset:38912
	ds_read_b128 v[232:235], v191 offset:39936
	global_load_lds_dwordx4 v[242:243], off
	v_lshl_add_u64 v[242:243], s[4:5], 0, v[156:157]
	s_mov_b32 m0, s17
	s_nop 0
	global_load_lds_dwordx4 v[242:243], off
	s_waitcnt vmcnt(8)
	s_waitcnt lgkmcnt(0)
	s_barrier
	s_setprio 1
	s_waitcnt lgkmcnt(0)
	v_mfma_f32_16x16x32_bf16 v[150:153], v[114:117], v[182:185], v[150:153]
	v_mfma_f32_16x16x32_bf16 v[146:149], v[122:125], v[182:185], v[146:149]
	v_mfma_f32_16x16x32_bf16 v[110:113], v[114:117], v[196:199], v[110:113]
	v_mfma_f32_16x16x32_bf16 v[106:109], v[122:125], v[196:199], v[106:109]
	v_mfma_f32_16x16x32_bf16 v[94:97], v[114:117], v[204:207], v[94:97]
	v_mfma_f32_16x16x32_bf16 v[90:93], v[122:125], v[204:207], v[90:93]
	v_mfma_f32_16x16x32_bf16 v[78:81], v[114:117], v[228:231], v[78:81]
	v_mfma_f32_16x16x32_bf16 v[74:77], v[122:125], v[228:231], v[74:77]
	v_mfma_f32_16x16x32_bf16 v[150:153], v[118:121], v[192:195], v[150:153]
	v_mfma_f32_16x16x32_bf16 v[146:149], v[126:129], v[192:195], v[146:149]
	v_mfma_f32_16x16x32_bf16 v[110:113], v[118:121], v[200:203], v[110:113]
	v_mfma_f32_16x16x32_bf16 v[106:109], v[126:129], v[200:203], v[106:109]
	v_mfma_f32_16x16x32_bf16 v[94:97], v[118:121], v[224:227], v[94:97]
	v_mfma_f32_16x16x32_bf16 v[90:93], v[126:129], v[224:227], v[90:93]
	v_mfma_f32_16x16x32_bf16 v[78:81], v[118:121], v[232:235], v[78:81]
	v_mfma_f32_16x16x32_bf16 v[74:77], v[126:129], v[232:235], v[74:77]
	s_setprio 0
	s_setprio 1
	v_mfma_f32_16x16x32_bf16 v[142:145], v[130:133], v[182:185], v[142:145]
	v_mfma_f32_16x16x32_bf16 v[138:141], v[174:177], v[182:185], v[138:141]
	v_mfma_f32_16x16x32_bf16 v[102:105], v[130:133], v[196:199], v[102:105]
	v_mfma_f32_16x16x32_bf16 v[98:101], v[174:177], v[196:199], v[98:101]
	v_mfma_f32_16x16x32_bf16 v[86:89], v[130:133], v[204:207], v[86:89]
	v_mfma_f32_16x16x32_bf16 v[82:85], v[174:177], v[204:207], v[82:85]
	v_mfma_f32_16x16x32_bf16 v[70:73], v[130:133], v[228:231], v[70:73]
	v_mfma_f32_16x16x32_bf16 v[66:69], v[174:177], v[228:231], v[66:69]
	v_mfma_f32_16x16x32_bf16 v[142:145], v[134:137], v[192:195], v[142:145]
	v_mfma_f32_16x16x32_bf16 v[138:141], v[178:181], v[192:195], v[138:141]
	v_mfma_f32_16x16x32_bf16 v[102:105], v[134:137], v[200:203], v[102:105]
	v_mfma_f32_16x16x32_bf16 v[98:101], v[178:181], v[200:203], v[98:101]
	v_mfma_f32_16x16x32_bf16 v[86:89], v[134:137], v[224:227], v[86:89]
	v_mfma_f32_16x16x32_bf16 v[82:85], v[178:181], v[224:227], v[82:85]
	v_mfma_f32_16x16x32_bf16 v[70:73], v[134:137], v[232:235], v[70:73]
	v_mfma_f32_16x16x32_bf16 v[66:69], v[178:181], v[232:235], v[66:69]
	s_setprio 0
	s_barrier
	s_add_i32 s4, s28, s13
	v_lshl_add_u64 v[186:187], v[186:187], 0, s[60:61]
	s_mov_b32 m0, s4
	ds_read_b128 v[182:185], v191 offset:49152
	ds_read_b128 v[192:195], v191 offset:50176
	ds_read_b128 v[196:199], v191 offset:51200
	ds_read_b128 v[200:203], v191 offset:52224
	ds_read_b128 v[204:207], v191 offset:53248
	ds_read_b128 v[224:227], v191 offset:54272
	ds_read_b128 v[228:231], v191 offset:55296
	ds_read_b128 v[232:235], v191 offset:56320
	global_load_lds_dwordx4 v[186:187], off
	s_add_i32 m0, s4, 0x2000
	s_add_u32 s2, s2, 0xb0080
	v_lshl_add_u64 v[186:187], v[236:237], 0, s[60:61]
	s_addc_u32 s3, s3, 0
	s_add_i32 s4, s29, s13
	global_load_lds_dwordx4 v[186:187], off
	v_lshl_add_u64 v[186:187], s[2:3], 0, v[0:1]
	s_mov_b32 m0, s4
	s_nop 0
	global_load_lds_dwordx4 v[186:187], off
	v_lshl_add_u64 v[186:187], s[2:3], 0, v[158:159]
	s_add_i32 m0, s4, 0x2000
	s_nop 0
	global_load_lds_dwordx4 v[186:187], off
	v_lshl_add_u64 v[186:187], v[238:239], 0, s[60:61]
	s_mov_b32 m0, s18
	s_nop 0
	global_load_lds_dwordx4 v[186:187], off
	v_lshl_add_u64 v[186:187], v[240:241], 0, s[60:61]
	s_mov_b32 m0, s19
	s_nop 0
	global_load_lds_dwordx4 v[186:187], off
	s_waitcnt vmcnt(8)
	s_waitcnt lgkmcnt(0)
	s_barrier
	s_setprio 1
	s_waitcnt lgkmcnt(0)
	v_mfma_f32_16x16x32_bf16 v[62:65], v[114:117], v[182:185], v[62:65]
	v_mfma_f32_16x16x32_bf16 v[58:61], v[122:125], v[182:185], v[58:61]
	v_mfma_f32_16x16x32_bf16 v[46:49], v[114:117], v[196:199], v[46:49]
	v_mfma_f32_16x16x32_bf16 v[42:45], v[122:125], v[196:199], v[42:45]
	v_mfma_f32_16x16x32_bf16 v[30:33], v[114:117], v[204:207], v[30:33]
	v_mfma_f32_16x16x32_bf16 v[26:29], v[122:125], v[204:207], v[26:29]
	v_mfma_f32_16x16x32_bf16 v[14:17], v[114:117], v[228:231], v[14:17]
	v_mfma_f32_16x16x32_bf16 v[10:13], v[122:125], v[228:231], v[10:13]
	v_mfma_f32_16x16x32_bf16 v[62:65], v[118:121], v[192:195], v[62:65]
	v_mfma_f32_16x16x32_bf16 v[58:61], v[126:129], v[192:195], v[58:61]
	v_mfma_f32_16x16x32_bf16 v[46:49], v[118:121], v[200:203], v[46:49]
	v_mfma_f32_16x16x32_bf16 v[42:45], v[126:129], v[200:203], v[42:45]
	v_mfma_f32_16x16x32_bf16 v[30:33], v[118:121], v[224:227], v[30:33]
	v_mfma_f32_16x16x32_bf16 v[26:29], v[126:129], v[224:227], v[26:29]
	v_mfma_f32_16x16x32_bf16 v[14:17], v[118:121], v[232:235], v[14:17]
	v_mfma_f32_16x16x32_bf16 v[10:13], v[126:129], v[232:235], v[10:13]
	s_setprio 0
	s_setprio 1
	v_mfma_f32_16x16x32_bf16 v[54:57], v[130:133], v[182:185], v[54:57]
	v_mfma_f32_16x16x32_bf16 v[50:53], v[174:177], v[182:185], v[50:53]
	v_mfma_f32_16x16x32_bf16 v[38:41], v[130:133], v[196:199], v[38:41]
	v_mfma_f32_16x16x32_bf16 v[34:37], v[174:177], v[196:199], v[34:37]
	v_mfma_f32_16x16x32_bf16 v[22:25], v[130:133], v[204:207], v[22:25]
	v_mfma_f32_16x16x32_bf16 v[18:21], v[174:177], v[204:207], v[18:21]
	v_mfma_f32_16x16x32_bf16 v[6:9], v[130:133], v[228:231], v[6:9]
	v_mfma_f32_16x16x32_bf16 v[2:5], v[174:177], v[228:231], v[2:5]
	v_mfma_f32_16x16x32_bf16 v[54:57], v[134:137], v[192:195], v[54:57]
	v_mfma_f32_16x16x32_bf16 v[50:53], v[178:181], v[192:195], v[50:53]
	v_mfma_f32_16x16x32_bf16 v[38:41], v[134:137], v[200:203], v[38:41]
	v_mfma_f32_16x16x32_bf16 v[34:37], v[178:181], v[200:203], v[34:37]
	v_mfma_f32_16x16x32_bf16 v[22:25], v[134:137], v[224:227], v[22:25]
	v_mfma_f32_16x16x32_bf16 v[18:21], v[178:181], v[224:227], v[18:21]
	v_mfma_f32_16x16x32_bf16 v[6:9], v[134:137], v[232:235], v[6:9]
	v_mfma_f32_16x16x32_bf16 v[2:5], v[178:181], v[232:235], v[2:5]
	s_setprio 0
	s_barrier
	s_add_i32 s27, s27, 2
	s_add_u32 s25, s25, 0x100
	s_addc_u32 s26, s26, 0
	s_cmp_gt_u32 s27, 41
	s_mov_b64 s[56:57], s[0:1]
	s_cbranch_scc0 .LBB0_662
	s_and_b64 vcc, exec, s[48:49]
	s_cbranch_vccz .LBB0_665
	s_barrier

.LBB0_697:
	s_ashr_i32 s45, s44, 31
	s_lshl_b64 s[4:5], s[44:45], 19
	v_readlane_b32 s24, v254, 43
	v_readlane_b32 s25, v254, 44
	s_add_u32 s4, s24, s4
	s_addc_u32 s5, s25, s5
	s_and_b64 s[24:25], s[40:41], exec
	s_cselect_b32 s24, s5, s7
	s_cselect_b32 s25, s4, s6
	s_ashr_i32 s39, s38, 31
	s_lshl_b64 s[28:29], s[38:39], 19
	s_add_u32 s48, s11, s28
	s_addc_u32 s49, s12, s29
	s_and_b64 s[28:29], s[40:41], exec
	s_cselect_b32 s28, s49, s1
	s_cselect_b32 s29, s48, s0
	s_add_u32 s56, s6, 0x40080
	s_addc_u32 s57, s7, 0
	s_add_u32 s34, s0, 0x100
	v_mov_b32_e32 v2, 0
	s_addc_u32 s35, s1, 0
	s_mov_b32 s39, -2
	v_mov_b32_e32 v3, v2
	v_mov_b32_e32 v4, v2
	v_mov_b32_e32 v5, v2
	v_mov_b32_e32 v6, v2
	v_mov_b32_e32 v7, v2
	v_mov_b32_e32 v8, v2
	v_mov_b32_e32 v9, v2
	v_mov_b32_e32 v18, v2
	v_mov_b32_e32 v19, v2
	v_mov_b32_e32 v20, v2
	v_mov_b32_e32 v21, v2
	v_mov_b32_e32 v22, v2
	v_mov_b32_e32 v23, v2
	v_mov_b32_e32 v24, v2
	v_mov_b32_e32 v25, v2
	v_mov_b32_e32 v34, v2
	v_mov_b32_e32 v35, v2
	v_mov_b32_e32 v36, v2
	v_mov_b32_e32 v37, v2
	v_mov_b32_e32 v38, v2
	v_mov_b32_e32 v39, v2
	v_mov_b32_e32 v40, v2
	v_mov_b32_e32 v41, v2
	v_mov_b32_e32 v50, v2
	v_mov_b32_e32 v51, v2
	v_mov_b32_e32 v52, v2
	v_mov_b32_e32 v53, v2
	v_mov_b32_e32 v54, v2
	v_mov_b32_e32 v55, v2
	v_mov_b32_e32 v56, v2
	v_mov_b32_e32 v57, v2
	v_mov_b32_e32 v10, v2
	v_mov_b32_e32 v11, v2
	v_mov_b32_e32 v12, v2
	v_mov_b32_e32 v13, v2
	v_mov_b32_e32 v14, v2
	v_mov_b32_e32 v15, v2
	v_mov_b32_e32 v16, v2
	v_mov_b32_e32 v17, v2
	v_mov_b32_e32 v26, v2
	v_mov_b32_e32 v27, v2
	v_mov_b32_e32 v28, v2
	v_mov_b32_e32 v29, v2
	v_mov_b32_e32 v30, v2
	v_mov_b32_e32 v31, v2
	v_mov_b32_e32 v32, v2
	v_mov_b32_e32 v33, v2
	v_mov_b32_e32 v42, v2
	v_mov_b32_e32 v43, v2
	v_mov_b32_e32 v44, v2
	v_mov_b32_e32 v45, v2
	v_mov_b32_e32 v46, v2
	v_mov_b32_e32 v47, v2
	v_mov_b32_e32 v48, v2
	v_mov_b32_e32 v49, v2
	v_mov_b32_e32 v58, v2
	v_mov_b32_e32 v59, v2
	v_mov_b32_e32 v60, v2
	v_mov_b32_e32 v61, v2
	v_mov_b32_e32 v62, v2
	v_mov_b32_e32 v63, v2
	v_mov_b32_e32 v64, v2
	v_mov_b32_e32 v65, v2
	v_mov_b32_e32 v66, v2
	v_mov_b32_e32 v67, v2
	v_mov_b32_e32 v68, v2
	v_mov_b32_e32 v69, v2
	v_mov_b32_e32 v70, v2
	v_mov_b32_e32 v71, v2
	v_mov_b32_e32 v72, v2
	v_mov_b32_e32 v73, v2
	v_mov_b32_e32 v82, v2
	v_mov_b32_e32 v83, v2
	v_mov_b32_e32 v84, v2
	v_mov_b32_e32 v85, v2
	v_mov_b32_e32 v86, v2
	v_mov_b32_e32 v87, v2
	v_mov_b32_e32 v88, v2
	v_mov_b32_e32 v89, v2
	v_mov_b32_e32 v98, v2
	v_mov_b32_e32 v99, v2
	v_mov_b32_e32 v100, v2
	v_mov_b32_e32 v101, v2
	v_mov_b32_e32 v102, v2
	v_mov_b32_e32 v103, v2
	v_mov_b32_e32 v104, v2
	v_mov_b32_e32 v105, v2
	v_mov_b32_e32 v114, v2
	v_mov_b32_e32 v115, v2
	v_mov_b32_e32 v116, v2
	v_mov_b32_e32 v117, v2
	v_mov_b32_e32 v118, v2
	v_mov_b32_e32 v119, v2
	v_mov_b32_e32 v120, v2
	v_mov_b32_e32 v121, v2
	v_mov_b32_e32 v74, v2
	v_mov_b32_e32 v75, v2
	v_mov_b32_e32 v76, v2
	v_mov_b32_e32 v77, v2
	v_mov_b32_e32 v78, v2
	v_mov_b32_e32 v79, v2
	v_mov_b32_e32 v80, v2
	v_mov_b32_e32 v81, v2
	v_mov_b32_e32 v90, v2
	v_mov_b32_e32 v91, v2
	v_mov_b32_e32 v92, v2
	v_mov_b32_e32 v93, v2
	v_mov_b32_e32 v94, v2
	v_mov_b32_e32 v95, v2
	v_mov_b32_e32 v96, v2
	v_mov_b32_e32 v97, v2
	v_mov_b32_e32 v106, v2
	v_mov_b32_e32 v107, v2
	v_mov_b32_e32 v108, v2
	v_mov_b32_e32 v109, v2
	v_mov_b32_e32 v110, v2
	v_mov_b32_e32 v111, v2
	v_mov_b32_e32 v112, v2
	v_mov_b32_e32 v113, v2
	v_mov_b32_e32 v122, v2
	v_mov_b32_e32 v123, v2
	v_mov_b32_e32 v124, v2
	v_mov_b32_e32 v125, v2
	v_mov_b32_e32 v126, v2
	v_mov_b32_e32 v127, v2
	v_mov_b32_e32 v128, v2
	v_mov_b32_e32 v129, v2
	s_mov_b64 s[60:61], 0x80
